# attention: cross-half max via v_permlane32_swap, packed f32 split to scalar ops, V fragments read as 8-byte halves (no cndmask), tile mask applied to lane max, waves of a workgroup share one head (tas
# speedup vs baseline: 1.0194x; 1.0048x over previous
; #define LAS __attribute__((address_space(3)))
; __device__ __forceinline__ int tid_() { int t = threadIdx.x; asm volatile("" : "+v"(t)); return t; }
; __device__ __forceinline__ int bid_() { int t = blockIdx.x; asm volatile("" : "+s"(t)); return t; }
; __device__ __forceinline__ void attn_all(KArgs& a, LAS unsigned char* lds, int l) {
;     const int tid = tid_(), lane = tid & 63, wave = __builtin_amdgcn_readfirstlane(tid >> 6), q32 = lane & 31, g = lane >> 5;
;     LAS float* rpb_s = (LAS float*)(lds + 1024);
;     for (int i = tid; i < 3720; i += 512) rpb_s[i] = a.na_rpb[l * 3720 + i] * 1.44269504f;
;     LAS unsigned char* wbuf = lds + 16384 + wave * 16384;
;     __syncthreads();
;     const bf16_t* PA = (const bf16_t*)(a.ws + OFF_R1); const bf16_t* VT = (const bf16_t*)(a.ws + OFF_VT); const bf16_t* KH = (const bf16_t*)(a.ws + OFF_KH); bf16_t* OA = (bf16_t*)(a.ws + OFF_R2 + 2 * SZ_ACT);
;     const int nb = nblk_(), bid = nb - 1 - bid_(), ntb = 1024 + (l < DEPTH - 1 ? 64 : 0);
;     const bool xl = (nb & 7) == 0;
;     const int gw = xl ? (bid >> 3) * 8 + wave : bid * 8 + wave, ngw = xl ? nb : nb * 8, tend = xl ? ntb : 8 * ntb;
;     for (int ti = gw; ti < tend; ti += ngw) {
;         const int b = xl ? (bid & 7) : ti / ntb, task = xl ? ti : ti - b * ntb;
;         int h, qtok, n_local = 0, krow_lo = 0, tc0 = 0, qrow_g = 0, qcol = 0, r0q = 0;
;         float cadd[16];
; #pragma unroll
;         for (int j = 0; j < 16; ++j) cadd[j] = 0.f;
;         if (task < 1024) {
;             h = task & 7; const int cb = (task >> 3) & 3, rp = task >> 5;
;             const int rr0 = 2 * rp; qrow_g = rr0 + (q32 >> 4); qcol = cb * 16 + (q32 & 15);
;             qtok = b * TPB + CTXL + qrow_g * 64 + qcol;
;             r0q = min(max(qrow_g - 4, 0), 56); const int csq = min(max(qcol - 8, 0), 48);
;             tc0 = min(max(cb * 16 - 8, 0), 32);
;             krow_lo = min(max(rr0 - 4, 0), 56); n_local = min(max(rr0 - 3, 0), 56) + 8 - krow_lo;
; #pragma unroll
;             for (int j = 0; j < 16; ++j) { const int ko = 8 * (j >> 2) + 4 * g + (j & 3); cadd[j] = (unsigned)(tc0 + ko - csq) < 16u ? 0.f : -1e30f; }
;         } else { const int j = task - 1024; h = j & 7; qtok = b * TPB + (j >> 3) * 32 + q32; }
;         const bf16_t* KHb = KH + (size_t)(b * 8 + h) * TPB * 64; const bf16_t* VTb = VT + (size_t)(b * 8 + h) * 544 * 512;
.LBB0_490:
	s_or_b64 exec, exec, s[0:1]
	s_waitcnt lgkmcnt(0)
	v_readlane_b32 s4, v237, 2
	v_readlane_b32 s5, v237, 3
	s_waitcnt vmcnt(0)
	s_barrier
	s_load_dwordx2 s[0:1], s[4:5], 0xf0
	s_waitcnt lgkmcnt(0)
	s_mov_b32 s1, s84
	s_not_b32 s1, s1
	s_ashr_i32 s8, s6, 6
	s_add_i32 s3, s0, s1
	s_cmp_lt_i32 s2, 3
	s_cselect_b32 s2, s95, 0x400
	s_and_b32 s9, s0, 7
	s_cmp_lg_u32 s9, 0
	s_cselect_b64 s[4:5], -1, 0
	s_and_b32 s22, s3, -8
	s_lshl_b32 s3, s3, 3
	s_lshl_b32 s23, s2, 3
	s_cmp_eq_u32 s9, 0
	s_cselect_b64 s[16:17], -1, 0
	s_and_b64 s[18:19], s[16:17], exec
	s_cselect_b32 s9, s22, s3
	s_cselect_b32 s3, s2, s23
	s_add_i32 s18, s9, s8
	s_cmp_ge_i32 s18, s3
	s_cbranch_scc1 .LBB0_524
	s_lshl_b32 s8, s8, 14
	s_add_i32 s19, s8, 0
	s_add_u32 s24, s14, 0x174f8000
	v_and_b32_e32 v5, 31, v2
	v_bfe_u32 v6, v2, 5, 1
	v_and_b32_e32 v7, 7, v2
	v_bfe_u32 v8, v2, 3, 2
	s_addc_u32 s25, s15, 0
	v_lshlrev_b32_e32 v152, 10, v8
	v_bfe_u32 v8, v5, 3, 1
	v_lshlrev_b32_e32 v153, 7, v7
	v_bitop3_b32 v7, v6, v2, 7 bitop3:0x78
	s_add_u32 s31, s14, 0x152f8000
	v_xor_b32_e32 v7, v7, v8
	s_addc_u32 s33, s15, 0
	s_lshl_b32 s22, s0, 3
	v_lshlrev_b32_e32 v154, 4, v7
	v_or_b32_e32 v7, 2, v6
	s_and_b64 s[8:9], s[16:17], exec
	v_bitop3_b32 v7, v2, v7, 7 bitop3:0x6c
	s_cselect_b32 s34, s0, s22
	v_xor_b32_e32 v7, v7, v8
	s_bfe_u32 s36, s6, 0x30006
	s_bfe_u32 s100, s18, 0x30003
	s_cmp_lg_u64 s[16:17], 0
	s_cselect_b32 s36, s100, s36
	s_and_b32 s35, s1, 7
	v_lshlrev_b32_e32 v150, 2, v6
	v_lshlrev_b32_e32 v0, 3, v6
	v_bfe_u32 v151, v2, 3, 3
	v_lshlrev_b32_e32 v155, 4, v7
	v_or_b32_e32 v7, 4, v6
	v_or_b32_e32 v6, 6, v6
	s_lshl_b32 s6, s36, 6
	s_lshl_b32 s0, s36, 7
	v_and_b32_e32 v3, 63, v2
	v_bfe_u32 v148, v2, 4, 1
	v_and_b32_e32 v149, 15, v2
	v_bitop3_b32 v4, v151, v2, 7 bitop3:0x78
	v_bitop3_b32 v7, v2, v7, 7 bitop3:0x6c
	v_bitop3_b32 v2, v2, v6, 7 bitop3:0x6c
	s_add_u32 s0, s14, s0
	v_xor_b32_e32 v2, v2, v8
	s_addc_u32 s1, s15, 0
	v_lshlrev_b32_e32 v102, 4, v3
	v_lshlrev_b32_e32 v157, 4, v2
	v_cmp_gt_u32_e64 s[40:41], 32, v3
	v_lshl_add_u64 v[2:3], s[0:1], 0, v[0:1]
	s_mov_b64 s[0:1], 0x1daf8000
	v_lshl_add_u64 v[104:105], v[2:3], 0, s[0:1]
	v_cvt_f32_u32_e32 v2, s2
	s_sub_i32 s0, 0, s2
	v_lshlrev_b32_e32 v100, 3, v4
	s_mul_i32 s8, s36, 0x744
	v_rcp_iflag_f32_e32 v2, v2
	v_xor_b32_e32 v4, 8, v100
	v_xor_b32_e32 v7, v7, v8
	s_add_i32 s38, s8, 0
	v_mul_f32_e32 v2, 0x4f7ffffe, v2
	v_cvt_u32_f32_e32 v2, v2
	v_or_b32_e32 v101, 0xfffff000, v5
	v_mov_b32_e32 v103, v1
	v_lshlrev_b32_e32 v156, 4, v7
	v_readfirstlane_b32 s1, v2
	s_mul_i32 s0, s0, s1
	s_mul_hi_u32 s0, s1, s0
	v_lshlrev_b32_e32 v158, 4, v5
	s_add_i32 s37, s1, s0
	s_addk_i32 s38, 0x43c
	s_lshl_b32 s6, s6, 1
	v_lshlrev_b32_e32 v106, 1, v0
	v_lshlrev_b32_e32 v108, 1, v4
	s_add_i32 s39, s19, 0x4400
	s_add_i32 s42, s19, 0x4800
	s_add_i32 s43, s19, 0x4c00
	s_add_i32 s44, s19, 0x5000
	s_add_i32 s45, s19, 0x5400
	s_add_i32 s46, s19, 0x5800
	s_add_i32 s47, s19, 0x5c00
	s_add_i32 s48, s19, 0x6400
	s_add_i32 s49, s19, 0x6800
	s_add_i32 s52, s19, 0x6c00
	s_add_i32 s53, s19, 0x7000
	s_add_i32 s54, s19, 0x7400
	s_add_i32 s55, s19, 0x7800
	s_add_i32 s56, s19, 0x7c00
	s_branch .LBB0_493

; __device__ __forceinline__ void attn_all(KArgs& a, LAS unsigned char* lds, int l) {
;     ...
;         if (task < 1024) {
;             h = task & 7; const int cb = (task >> 3) & 3, rp = task >> 5;
;             const int rr0 = 2 * rp; qrow_g = rr0 + (q32 >> 4); qcol = cb * 16 + (q32 & 15);
;             qtok = b * TPB + CTXL + qrow_g * 64 + qcol;
;             r0q = min(max(qrow_g - 4, 0), 56); const int csq = min(max(qcol - 8, 0), 48);
;             tc0 = min(max(cb * 16 - 8, 0), 32);
;             krow_lo = min(max(rr0 - 4, 0), 56); n_local = min(max(rr0 - 3, 0), 56) + 8 - krow_lo;
; #pragma unroll
;             for (int j = 0; j < 16; ++j) { const int ko = 8 * (j >> 2) + 4 * g + (j & 3); cadd[j] = (unsigned)(tc0 + ko - csq) < 16u ? 0.f : -1e30f; }
;         } else { const int j = task - 1024; h = j & 7; qtok = b * TPB + (j >> 3) * 32 + q32; }
.LBB0_495:
	s_mul_i32 s9, s8, s2
	s_and_b64 s[0:1], s[16:17], exec
	s_cselect_b32 s0, 0, s9
	s_sub_i32 s22, s18, s0
	s_lshr_b32 s100, s19, 11
	s_andn2_b32 s101, s22, 56
	s_or_b32 s101, s101, s100
	s_cmp_lg_u64 s[16:17], 0
	s_cselect_b32 s101, s101, s22
	s_mov_b64 s[0:1], -1
	s_cmpk_gt_i32 s22, 0x3ff
	s_mul_i32 s9, s8, 0x1100
	s_cbranch_scc0 .LBB0_497
	s_lshl_b32 s0, s101, 2
	s_andn2_b32 s0, s0, 31
	s_add_i32 s0, s0, s9
	v_add_u32_e32 v110, s0, v101
	s_mov_b64 s[0:1], 0
.LBB0_497:
	s_andn2_b64 vcc, exec, s[0:1]
	s_cbranch_vccnz .LBB0_499
	s_lshl_b32 s1, s101, 1
	s_and_b32 s1, s1, 48
	v_or_b32_e32 v2, s1, v149
	v_sub_u32_e64 v6, s1, 8 clamp
	v_max_i32_e32 v5, 8, v2
	v_readfirstlane_b32 s1, v6
	v_add_u32_e32 v5, -8, v5
	s_min_u32 s61, s1, 32
	v_min_u32_e32 v5, 48, v5
	v_or_b32_e32 v6, s61, v150
	v_sub_u32_e32 v5, v6, v5
	v_add_u32_e32 v6, 1, v5
	v_cmp_gt_u32_e32 vcc, 16, v5
	v_add_u32_e32 v7, 3, v5
	v_or_b32_e32 v3, s9, v2
	v_cndmask_b32_e64 v112, v228, 0, vcc
	v_cmp_gt_u32_e32 vcc, 16, v6
	v_add_u32_e32 v6, 2, v5
	s_movk_i32 s9, 0xffef
	v_cndmask_b32_e64 v113, v228, 0, vcc
	v_cmp_gt_u32_e32 vcc, 16, v6
	v_add_u32_e32 v6, 8, v5
	s_ashr_i32 s0, s101, 4
	v_cndmask_b32_e64 v114, v228, 0, vcc
	v_cmp_gt_u32_e32 vcc, 16, v7
	v_add_u32_e32 v7, 9, v5
	s_and_b32 s0, s0, -2
	v_cndmask_b32_e64 v115, v228, 0, vcc
	v_cmp_gt_u32_e32 vcc, 16, v6
	v_add_u32_e32 v6, 10, v5
	v_or_b32_e32 v0, s0, v148
	v_cndmask_b32_e64 v116, v228, 0, vcc
	v_cmp_gt_u32_e32 vcc, 16, v7
	v_add_u32_e32 v7, 11, v5
	s_max_i32 s1, s0, 4
	v_cndmask_b32_e64 v117, v228, 0, vcc
	v_cmp_gt_u32_e32 vcc, 16, v6
	v_add_u32_e32 v6, 17, v5
	s_max_i32 s0, s0, 3
	v_cndmask_b32_e64 v118, v228, 0, vcc
	v_cmp_gt_u32_e32 vcc, 16, v7
	v_add_u32_e32 v7, 19, v5
	s_add_i32 s1, s1, -4
	v_cndmask_b32_e64 v119, v228, 0, vcc
	v_cmp_lt_u32_e32 vcc, s9, v5
	s_add_i32 s0, s0, -3
	v_max_i32_e32 v4, 4, v0
	v_cndmask_b32_e64 v120, v228, 0, vcc
	v_cmp_gt_u32_e32 vcc, 16, v6
	v_add_u32_e32 v6, 18, v5
	s_min_u32 s0, s0, 56
	v_cndmask_b32_e64 v121, v228, 0, vcc
	v_cmp_gt_u32_e32 vcc, 16, v6
	v_add_u32_e32 v6, 24, v5
	s_min_u32 s59, s1, 56
	v_cndmask_b32_e64 v122, v228, 0, vcc
	v_cmp_gt_u32_e32 vcc, 16, v7
	v_add_u32_e32 v7, 25, v5
	v_add_u32_e32 v4, -4, v4
	v_cndmask_b32_e64 v123, v228, 0, vcc
	v_cmp_gt_u32_e32 vcc, 16, v6
	v_add_u32_e32 v6, 26, v5
	v_add_u32_e32 v5, 27, v5
	v_cndmask_b32_e64 v124, v228, 0, vcc
	v_cmp_gt_u32_e32 vcc, 16, v7
	s_sub_i32 s0, s0, s59
	s_add_i32 s58, s0, 8
	v_cndmask_b32_e64 v125, v228, 0, vcc
	v_cmp_gt_u32_e32 vcc, 16, v6
	s_nop 1
	v_cndmask_b32_e64 v126, v228, 0, vcc
	v_cmp_gt_u32_e32 vcc, 16, v5
	v_lshlrev_b32_e32 v5, 6, v0
	v_sub_u32_e32 v0, 7, v0
	v_cndmask_b32_e64 v127, v228, 0, vcc
	v_add3_u32 v110, v3, v5, s96
	v_min_u32_e32 v3, 56, v4
	v_mul_lo_u32 v4, v0, 31
	s_branch .LBB0_500

; #define LAS __attribute__((address_space(3)))
; __device__ __forceinline__ void attn_read_tile(const LAS unsigned char* buf, int lane, int q32, int g, bf16x8 (&kf)[4], bf16x8 (&vf)[2][2]) {
;     const int ki = q32 >> 3, kl = q32 & 7;
; #pragma unroll
;     for (int ks = 0; ks < 4; ++ks) kf[ks] = *(const LAS bf16x8*)(buf + ki * 1024 + (kl * 8 + ((2 * ks + g) ^ kl ^ (ki & 1))) * 16);
; #pragma unroll
;     for (int d = 0; d < 2; ++d)
; #pragma unroll
;         for (int s2 = 0; s2 < 2; ++s2) {
;             const u32x4 c0 = *(const LAS u32x4*)(buf + 4096 + (2 * s2) * 1024 + (32 * d + q32) * 16), c1 = *(const LAS u32x4*)(buf + 4096 + (2 * s2 + 1) * 1024 + (32 * d + q32) * 16);
;             const u32x4 w = {g ? c0.z : c0.x, g ? c0.w : c0.y, g ? c1.z : c1.x, g ? c1.w : c1.y}; vf[d][s2] = __builtin_bit_cast(bf16x8, w);
;         }
.LBB0_510:
	s_and_b32 s0, s9, 0x2000
	s_add_i32 s61, s19, s0
	v_add3_u32 v0, s61, v152, v153
	s_waitcnt vmcnt(8)
	v_add_u32_e32 v2, v0, v154
	ds_read_b128 v[2:5], v2 offset:16384
	v_add_u32_e32 v6, v0, v155
	ds_read_b128 v[6:9], v6 offset:16384
	v_add_u32_e32 v194, v0, v156
	ds_read_b128 v[194:197], v194 offset:16384
	v_add_u32_e32 v0, v0, v157
	ds_read_b128 v[134:137], v0 offset:16384
	v_and_b32_e32 v199, 32, v217
	v_lshrrev_b32_e32 v199, 2, v199
	v_add3_u32 v198, s61, v158, v199
	ds_read_b64 v[92:93], v198 offset:20480
	ds_read_b64 v[96:97], v198 offset:20992
	ds_read_b64 v[94:95], v198 offset:21504
	ds_read_b64 v[98:99], v198 offset:22016
	ds_read_b64 v[80:81], v198 offset:22528
	ds_read_b64 v[84:85], v198 offset:23040
	ds_read_b64 v[82:83], v198 offset:23552
	ds_read_b64 v[86:87], v198 offset:24064
	s_add_i32 s0, s23, 2
	s_min_i32 s63, s0, s60
	s_cmp_ge_i32 s0, s58
	s_mov_b64 s[0:1], -1
	s_waitcnt lgkmcnt(10)
	v_mfma_f32_32x32x16_bf16 v[48:63], v[2:5], v[72:75], 0
	v_mfma_f32_32x32x16_bf16 v[48:63], v[6:9], v[64:67], v[48:63]
	s_waitcnt lgkmcnt(8)
	v_mfma_f32_32x32x16_bf16 v[48:63], v[194:197], v[68:71], v[48:63]
	v_mfma_f32_32x32x16_bf16 v[48:63], v[134:137], v[76:79], v[48:63]
	s_waitcnt lgkmcnt(0)
	s_cbranch_scc0 .LBB0_512
	s_sub_i32 s0, s63, s58
	s_lshl_b32 s62, s0, 5
	s_mov_b64 s[0:1], 0

; #define LAS __attribute__((address_space(3)))
; __device__ __forceinline__ void attn_all(KArgs& a, LAS unsigned char* lds, int l) {
;     ...
;             attn_dma_tile(KHb, VTb, tile_tt(t + 2), lane, wbuf + (t & 1) * 8192);
;             float sv[16];
;             if (t < n_local) {
;                 const int krow = krow_lo + t; const float radd = (unsigned)(krow - r0q) < 8u ? 0.f : -1e30f;
;                 const LAS float* bp = bp0 + krow * 31;
;                 float bv[16];
; #pragma unroll
;                 for (int j = 0; j < 16; ++j) bv[j] = bp[8 * (j >> 2) + (j & 3)];
; #pragma unroll
;                 for (int j = 0; j < 16; ++j) sv[j] = fmaf(S[j], 0.125f * 1.44269504f, bv[j] + (cadd[j] + radd));
;             } else {
; #pragma unroll
;                 for (int j = 0; j < 16; ++j) sv[j] = S[j] * (0.125f * 1.44269504f);
;             }
;             float mx = sv[0];
; #pragma unroll
;             for (int j = 1; j < 16; ++j) mx = fmaxf(mx, sv[j]);
;             mx = fmaxf(mx, __shfl_xor(mx, 32));
;             const float mnew = fmaxf(mrun, mx);
;             if (__any(mnew > mrun)) {
;                 const float resc = __builtin_amdgcn_exp2f(mrun - mnew);
;                 lsum *= resc;
; #pragma unroll
;                 for (int j = 0; j < 16; ++j) { O0[j] *= resc; O1[j] *= resc; }
;                 mrun = mnew;
;             }
.LBB0_514:
	v_add_u32_e32 v14, s62, v151
	v_ashrrev_i32_e32 v15, 31, v14
	v_lshlrev_b64 v[134:135], 7, v[14:15]
	v_lshl_add_u64 v[134:135], v[128:129], 0, v[134:135]
	s_add_i32 m0, s61, 0x4000
	s_ashr_i32 s0, s62, 3
	global_load_lds_dwordx4 v[134:135], off
	v_add_u32_e32 v134, 8, v14
	v_ashrrev_i32_e32 v135, 31, v134
	v_lshlrev_b64 v[134:135], 7, v[134:135]
	v_lshl_add_u64 v[134:135], v[130:131], 0, v[134:135]
	s_add_i32 m0, s61, 0x4400
	s_ashr_i32 s1, s0, 31
	global_load_lds_dwordx4 v[134:135], off
	v_add_u32_e32 v134, 16, v14
	v_ashrrev_i32_e32 v135, 31, v134
	v_add_u32_e32 v14, 24, v14
	v_lshlrev_b64 v[134:135], 7, v[134:135]
	v_ashrrev_i32_e32 v15, 31, v14
	v_lshl_add_u64 v[134:135], v[128:129], 0, v[134:135]
	s_add_i32 m0, s61, 0x4800
	v_lshlrev_b64 v[14:15], 7, v[14:15]
	global_load_lds_dwordx4 v[134:135], off
	v_lshl_add_u64 v[14:15], v[130:131], 0, v[14:15]
	s_add_i32 m0, s61, 0x4c00
	s_lshl_b64 s[0:1], s[0:1], 10
	global_load_lds_dwordx4 v[14:15], off
	v_lshl_add_u64 v[14:15], v[132:133], 0, s[0:1]
	s_add_i32 m0, s61, 0x5000
	v_lshl_add_u64 v[134:135], v[14:15], 0, s[10:11]
	global_load_lds_dwordx4 v[14:15], off
	s_add_i32 m0, s61, 0x5400
	s_mov_b64 s[0:1], -1
	global_load_lds_dwordx4 v[134:135], off
	v_lshl_add_u64 v[134:135], v[14:15], 0, s[26:27]
	s_add_i32 m0, s61, 0x5800
	v_lshl_add_u64 v[14:15], v[14:15], 0, s[28:29]
	global_load_lds_dwordx4 v[134:135], off
	s_add_i32 m0, s61, 0x5c00
	s_cmp_lt_i32 s23, s58
	global_load_lds_dwordx4 v[14:15], off
	s_cbranch_scc1 .LBB0_516
	v_mul_f32_e32 v14, s30, v48
	v_mul_f32_e32 v15, s30, v49
	v_mul_f32_e32 v134, s30, v50
	v_mul_f32_e32 v135, s30, v51
	v_mul_f32_e32 v136, s30, v52
	v_mul_f32_e32 v137, s30, v53
	v_mul_f32_e32 v138, s30, v54
	v_mul_f32_e32 v139, s30, v55
	v_mul_f32_e32 v140, s30, v56
	v_mul_f32_e32 v141, s30, v57
	v_mul_f32_e32 v142, s30, v58
	v_mul_f32_e32 v143, s30, v59
	v_mul_f32_e32 v144, s30, v60
	v_mul_f32_e32 v145, s30, v61
	v_mul_f32_e32 v146, s30, v62
	v_mul_f32_e32 v147, s30, v63
	s_mov_b64 s[100:101], -1
	s_mov_b64 s[0:1], 0
.LBB0_516:
	s_andn2_b64 vcc, exec, s[0:1]
	s_cbranch_vccnz .LBB0_518
	ds_read2_b32 v[162:163], v109 offset1:1
	ds_read2_b32 v[164:165], v109 offset0:2 offset1:3
	ds_read2_b32 v[166:167], v109 offset0:8 offset1:9
	ds_read2_b32 v[168:169], v109 offset0:10 offset1:11
	ds_read2_b32 v[170:171], v109 offset0:16 offset1:17
	ds_read2_b32 v[172:173], v109 offset0:18 offset1:19
	ds_read2_b32 v[174:175], v109 offset0:24 offset1:25
	ds_read2_b32 v[176:177], v109 offset0:26 offset1:27
	v_add_u32_e32 v0, s23, v159
	v_cmp_gt_u32_e64 s[100:101], 8, v0
	s_waitcnt lgkmcnt(7)
	v_add_f32_e32 v178, v112, v162
	v_add_f32_e32 v179, v113, v163
	s_waitcnt lgkmcnt(6)
	v_add_f32_e32 v180, v114, v164
	v_add_f32_e32 v181, v115, v165
	v_fma_f32 v14, v48, s30, v178
	v_fma_f32 v15, v49, s30, v179
	s_waitcnt lgkmcnt(5)
	v_add_f32_e32 v182, v116, v166
	v_add_f32_e32 v183, v117, v167
	v_fma_f32 v134, v50, s30, v180
	v_fma_f32 v135, v51, s30, v181
	s_waitcnt lgkmcnt(4)
	v_add_f32_e32 v184, v118, v168
	v_add_f32_e32 v185, v119, v169
	v_fma_f32 v136, v52, s30, v182
	v_fma_f32 v137, v53, s30, v183
	s_waitcnt lgkmcnt(3)
	v_add_f32_e32 v186, v120, v170
	v_add_f32_e32 v187, v121, v171
	v_fma_f32 v138, v54, s30, v184
	v_fma_f32 v139, v55, s30, v185
	s_waitcnt lgkmcnt(2)
	v_add_f32_e32 v188, v122, v172
	v_add_f32_e32 v189, v123, v173
	v_fma_f32 v140, v56, s30, v186
	v_fma_f32 v141, v57, s30, v187
	s_waitcnt lgkmcnt(1)
	v_add_f32_e32 v190, v124, v174
	v_add_f32_e32 v191, v125, v175
	v_fma_f32 v142, v58, s30, v188
	v_fma_f32 v143, v59, s30, v189
	s_waitcnt lgkmcnt(0)
	v_add_f32_e32 v192, v126, v176
	v_add_f32_e32 v193, v127, v177
	v_fma_f32 v144, v60, s30, v190
	v_fma_f32 v145, v61, s30, v191
	s_nop 0
	v_fma_f32 v146, v62, s30, v192
	v_fma_f32 v147, v63, s30, v193
.LBB0_518:
	v_max_f32_e32 v0, v14, v15
	v_max3_f32 v0, v0, v134, v135
	v_max3_f32 v0, v0, v136, v137
	v_max3_f32 v0, v0, v138, v139
	v_max3_f32 v0, v0, v140, v141
	v_max3_f32 v0, v0, v142, v143
	v_max3_f32 v0, v0, v144, v145
	v_max3_f32 v0, v0, v146, v147
	v_cndmask_b32_e64 v0, v228, v0, s[100:101]
	v_mov_b32_e32 v48, v0
	v_mov_b32_e32 v49, v0
	s_nop 1
	v_permlane32_swap_b32 v48, v49
	v_max3_f32 v0, v160, v48, v49
	v_cmp_gt_f32_e32 vcc, v0, v160
	s_cbranch_vccz .LBB0_520
	v_sub_f32_e32 v48, v160, v0
	v_exp_f32_e32 v48, v48
	s_nop 0
	v_mul_f32_e32 v107, v107, v48
	v_mul_f32_e32 v46, v46, v48
	v_mul_f32_e32 v47, v47, v48
	v_mul_f32_e32 v44, v44, v48
	v_mul_f32_e32 v45, v45, v48
	v_mul_f32_e32 v42, v42, v48
	v_mul_f32_e32 v43, v43, v48
	v_mul_f32_e32 v40, v40, v48
	v_mul_f32_e32 v41, v41, v48
	v_mul_f32_e32 v38, v38, v48
	v_mul_f32_e32 v39, v39, v48
	v_mul_f32_e32 v36, v36, v48
	v_mul_f32_e32 v37, v37, v48
	v_mul_f32_e32 v34, v34, v48
	v_mul_f32_e32 v35, v35, v48
	v_mul_f32_e32 v32, v32, v48
	v_mul_f32_e32 v33, v33, v48
	v_mul_f32_e32 v30, v30, v48
	v_mul_f32_e32 v31, v31, v48
	v_mul_f32_e32 v28, v28, v48
	v_mul_f32_e32 v29, v29, v48
	v_mul_f32_e32 v26, v26, v48
	v_mul_f32_e32 v27, v27, v48
	v_mul_f32_e32 v24, v24, v48
	v_mul_f32_e32 v25, v25, v48
	v_mul_f32_e32 v22, v22, v48
	v_mul_f32_e32 v23, v23, v48
	v_mul_f32_e32 v20, v20, v48
	v_mul_f32_e32 v21, v21, v48
	v_mul_f32_e32 v18, v18, v48
	v_mul_f32_e32 v19, v19, v48
	v_mul_f32_e32 v16, v16, v48
	v_mul_f32_e32 v17, v17, v48
	s_branch .LBB0_521

; __device__ __forceinline__ unsigned pk2(float lo, float hi) { const f32x2 v = {lo, hi}; return __builtin_bit_cast(unsigned, __builtin_convertvector(v, bf16v2_t)); }
; #define MFMA32(a, b, c) __builtin_amdgcn_mfma_f32_32x32x16_bf16((a), (b), (c), 0, 0, 0)
; __device__ __forceinline__ void attn_all(KArgs& a, LAS unsigned char* lds, int l) {
;     ...
;             const float mnew = fmaxf(mrun, mx);
;             if (__any(mnew > mrun)) {
;                 const float resc = __builtin_amdgcn_exp2f(mrun - mnew);
;                 lsum *= resc;
; #pragma unroll
;                 for (int j = 0; j < 16; ++j) { O0[j] *= resc; O1[j] *= resc; }
;                 mrun = mnew;
;             }
;             float p[16], ps = 0.f;
; #pragma unroll
;             for (int j = 0; j < 16; ++j) { p[j] = __builtin_amdgcn_exp2f(sv[j] - mrun); ps += p[j]; }
;             lsum += ps;
;             const u32x4 w0 = {pk2(p[0], p[1]), pk2(p[2], p[3]), pk2(p[4], p[5]), pk2(p[6], p[7])}, w1 = {pk2(p[8], p[9]), pk2(p[10], p[11]), pk2(p[12], p[13]), pk2(p[14], p[15])};
;             const bf16x8 pb0 = __builtin_bit_cast(bf16x8, w0), pb1 = __builtin_bit_cast(bf16x8, w1);
;             O0 = MFMA32(vf[0][0], pb0, O0); O0 = MFMA32(vf[0][1], pb1, O0);
;             O1 = MFMA32(vf[1][0], pb0, O1); O1 = MFMA32(vf[1][1], pb1, O1);
.LBB0_521:
	v_cndmask_b32_e64 v161, -v228, v0, s[100:101]
	v_sub_f32_e32 v14, v14, v161
	v_exp_f32_e32 v14, v14
	v_sub_f32_e32 v15, v15, v161
	v_exp_f32_e32 v15, v15
	v_sub_f32_e32 v48, v134, v161
	v_exp_f32_e32 v55, v48
	v_sub_f32_e32 v48, v135, v161
	v_exp_f32_e32 v56, v48
	v_sub_f32_e32 v48, v136, v161
	v_add_f32_e32 v49, v15, v14
	v_exp_f32_e32 v57, v48
	v_sub_f32_e32 v48, v137, v161
	v_exp_f32_e32 v58, v48
	v_add_f32_e32 v48, v55, v49
	v_sub_f32_e32 v49, v138, v161
	v_exp_f32_e32 v49, v49
	v_sub_f32_e32 v50, v139, v161
	v_add_f32_e32 v48, v56, v48
	v_exp_f32_e32 v59, v50
	v_sub_f32_e32 v50, v140, v161
	v_add_f32_e32 v48, v57, v48
	v_exp_f32_e32 v60, v50
	v_sub_f32_e32 v50, v141, v161
	v_add_f32_e32 v48, v58, v48
	v_exp_f32_e32 v61, v50
	v_add_f32_e32 v48, v49, v48
	v_add_f32_e32 v48, v59, v48
	v_add_f32_e32 v48, v60, v48
	v_add_f32_e32 v62, v61, v48
	v_sub_f32_e32 v48, v142, v161
	v_exp_f32_e32 v63, v48
	v_sub_f32_e32 v48, v143, v161
	v_exp_f32_e32 v134, v48
	v_sub_f32_e32 v48, v144, v161
	v_cvt_pk_bf16_f32 v54, v14, v15
	v_cvt_pk_bf16_f32 v55, v55, v56
	v_cvt_pk_bf16_f32 v56, v57, v58
	v_cvt_pk_bf16_f32 v57, v49, v59
	v_exp_f32_e32 v135, v48
	v_sub_f32_e32 v48, v145, v161
	v_mfma_f32_32x32x16_bf16 v[32:47], v[92:95], v[54:57], v[32:47]
	v_exp_f32_e32 v136, v48
	v_sub_f32_e32 v48, v146, v161
	v_exp_f32_e32 v137, v48
	v_sub_f32_e32 v48, v147, v161
	v_exp_f32_e32 v138, v48
	v_mfma_f32_32x32x16_bf16 v[16:31], v[96:99], v[54:57], v[16:31]
	v_cvt_pk_bf16_f32 v58, v60, v61
	v_cvt_pk_bf16_f32 v59, v63, v134
	v_cvt_pk_bf16_f32 v60, v135, v136
	v_cvt_pk_bf16_f32 v61, v137, v138
	v_add_f32_e32 v14, v63, v62
	v_add_f32_e32 v14, v134, v14
	v_mfma_f32_32x32x16_bf16 v[32:47], v[80:83], v[58:61], v[32:47]
	v_add_f32_e32 v14, v135, v14
	v_add_f32_e32 v6, v136, v14
	v_add_f32_e32 v6, v137, v6
	v_add_f32_e32 v6, v138, v6
	s_add_i32 s23, s23, 1
	s_addk_i32 s9, 0x2000
	v_add_f32_e32 v107, v107, v6
	v_mfma_f32_32x32x16_bf16 v[16:31], v[84:87], v[58:61], v[16:31]
	s_cmp_eq_u32 s8, s23
	v_add_u32_e32 v109, 0x7c, v109
	s_cbranch_scc1 .LBB0_492
	v_mov_b32_e32 v160, v0
	s_branch .LBB0_510
